# v25 + MLA loop: running-max copy removed from the alpha chain (one VALU per iteration)
# baseline (speedup 1.0000x reference)
; #define LAS __attribute__((address_space(3)))
; __device__ __forceinline__ void finishSM(f32x16& p0, f32x16& p1, float alpha, float& l_reg, bf16x8& pa0, bf16x8& pa1, bf16x8& pa2, bf16x8& pa3) {
; #pragma unroll
;   for (int r = 0; r < 16; ++r) p1[r] = __builtin_amdgcn_exp2f(p1[r]);
;   float ps = 0;
; #pragma unroll
;   for (int r = 0; r < 16; ++r) ps += p0[r];
; #pragma unroll
;   for (int r = 0; r < 16; ++r) ps += p1[r];
;   { auto rr = __builtin_amdgcn_permlane32_swap(__float_as_uint(ps), __float_as_uint(ps), false, false);
;     ps = __uint_as_float(rr[0]) + __uint_as_float(rr[1]); }
;   l_reg = l_reg * alpha + ps;
;     ...
;   PK4(p0, 0, pa0); PK4(p0, 8, pa1); PK4(p1, 0, pa2); PK4(p1, 8, pa3);
; template <int MODE>
; __device__ __forceinline__ void qkt(f32x16& p0, f32x16& p1, const LAS unsigned char* Ks, const LAS unsigned char* Krs, const LAS unsigned char* qrf, const bf16x8* qr, int r32, int hi, int lane) {
;   p0 = f32x16{}; p1 = f32x16{};
; #pragma unroll
;   for (int d0 = 0; d0 < 8; ++d0) { const int cb = (d0 * 16 + hi * 8) * 2;
;     const bf16x8 b0 = *(const LAS bf16x8*)(Ks + KSWZ(r32, cb));
;     const bf16x8 b1 = *(const LAS bf16x8*)(Ks + KSWZ(32 + r32, cb));
;     p0 = __builtin_amdgcn_mfma_f32_32x32x16_bf16(b0, qr[d0], p0, 0, 0, 0);
;     p1 = __builtin_amdgcn_mfma_f32_32x32x16_bf16(b1, qr[d0], p1, 0, 0, 0); }
;   if constexpr (MODE == 0) {
; #pragma unroll
;     for (int d0 = 0; d0 < 4; ++d0) { const int ch = d0 * 2 + hi;
;       const bf16x8 b0 = *(const LAS bf16x8*)(Krs + KRSWZ(r32, ch));
;       const bf16x8 b1 = *(const LAS bf16x8*)(Krs + KRSWZ(32 + r32, ch));
;       const bf16x8 q = *(const LAS bf16x8*)(qrf + (d0 * 64 + lane) * 16);
;       p0 = __builtin_amdgcn_mfma_f32_32x32x16_bf16(b0, q, p0, 0, 0, 0);
;       p1 = __builtin_amdgcn_mfma_f32_32x32x16_bf16(b1, q, p1, 0, 0, 0); }
;   }
; }
.LBB0_939:
	ds_read_b128 v[64:67], v158 offset:49152
	ds_read_b128 v[68:71], v158 offset:57344
	s_waitcnt lgkmcnt(1)
	v_mfma_f32_32x32x16_bf16 v[80:95], v[64:67], v[100:103], 0
	s_waitcnt lgkmcnt(0)
	v_mfma_f32_32x32x16_bf16 v[64:79], v[68:71], v[100:103], 0
	ds_read_b128 v[206:209], v160 offset:49152
	ds_read_b128 v[210:213], v160 offset:57344
	v_exp_f32_e32 v181, v144
	v_exp_f32_e32 v190, v145
	v_add_f32_e32 v144, 0, v197
	v_add_u32_e32 v180, v175, v166
	v_add_u32_e32 v179, v175, v168
	v_add_u32_e32 v178, v175, v170
	v_add_u32_e32 v177, v175, v172
	v_add_f32_e32 v144, v198, v144
	s_waitcnt lgkmcnt(1)
	v_mfma_f32_32x32x16_bf16 v[80:95], v[206:209], v[116:119], v[80:95]
	s_waitcnt lgkmcnt(0)
	v_mfma_f32_32x32x16_bf16 v[64:79], v[210:213], v[116:119], v[64:79]
	ds_read_b128 v[206:209], v161 offset:49152
	ds_read_b128 v[210:213], v161 offset:57344
	v_exp_f32_e32 v191, v142
	v_exp_f32_e32 v205, v143
	v_add_f32_e32 v142, v199, v144
	v_add_f32_e32 v142, v201, v142
	v_add_f32_e32 v142, v202, v142
	v_add_f32_e32 v142, v204, v142
	v_add_f32_e32 v142, v200, v142
	v_add_f32_e32 v214, v203, v142
	s_waitcnt lgkmcnt(1)
	v_mfma_f32_32x32x16_bf16 v[80:95], v[206:209], v[124:127], v[80:95]
	s_waitcnt lgkmcnt(0)
	v_mfma_f32_32x32x16_bf16 v[64:79], v[210:213], v[124:127], v[64:79]
	ds_read_b128 v[142:145], v164 offset:49152
	ds_read_b128 v[206:209], v164 offset:57344
	v_exp_f32_e32 v210, v138
	v_exp_f32_e32 v211, v139
	v_add_f32_e32 v138, v193, v214
	v_add_f32_e32 v138, v194, v138
	v_add_f32_e32 v138, v195, v138
	v_add_f32_e32 v138, v196, v138
	v_add_f32_e32 v138, v182, v138
	v_add_f32_e32 v138, v183, v138
	s_waitcnt lgkmcnt(1)
	v_mfma_f32_32x32x16_bf16 v[80:95], v[142:145], v[120:123], v[80:95]
	s_waitcnt lgkmcnt(0)
	v_mfma_f32_32x32x16_bf16 v[64:79], v[206:209], v[120:123], v[64:79]
	ds_read_b128 v[142:145], v165 offset:49152
	ds_read_b128 v[206:209], v165 offset:57344
	v_exp_f32_e32 v212, v136
	v_exp_f32_e32 v213, v137
	v_add_f32_e32 v136, v184, v138
	v_add_f32_e32 v136, v192, v136
	v_add_f32_e32 v136, v181, v136
	v_add_f32_e32 v136, v190, v136
	v_add_f32_e32 v136, v191, v136
	v_add_f32_e32 v214, v205, v136
	s_waitcnt lgkmcnt(1)
	v_mfma_f32_32x32x16_bf16 v[80:95], v[142:145], v[112:115], v[80:95]
	s_waitcnt lgkmcnt(0)
	v_mfma_f32_32x32x16_bf16 v[64:79], v[206:209], v[112:115], v[64:79]
	ds_read_b128 v[136:139], v163 offset:49152
	ds_read_b128 v[142:145], v163 offset:57344
	v_exp_f32_e32 v206, v130
	v_exp_f32_e32 v207, v131
	v_add_f32_e32 v130, v210, v214
	v_add_f32_e32 v130, v211, v130
	v_add_f32_e32 v130, v212, v130
	v_add_f32_e32 v130, v213, v130
	v_add_f32_e32 v130, v206, v130
	v_add_f32_e32 v130, v207, v130
	s_waitcnt lgkmcnt(1)
	v_mfma_f32_32x32x16_bf16 v[80:95], v[136:139], v[108:111], v[80:95]
	s_waitcnt lgkmcnt(0)
	v_mfma_f32_32x32x16_bf16 v[64:79], v[142:145], v[108:111], v[64:79]
	ds_read_b128 v[136:139], v162 offset:49152
	ds_read_b128 v[142:145], v162 offset:57344
	v_exp_f32_e32 v208, v128
	v_exp_f32_e32 v209, v129
	v_cvt_pk_bf16_f32 v129, v199, v201
	v_cvt_pk_bf16_f32 v131, v200, v203
	v_add_f32_e32 v128, v208, v130
	v_add_f32_e32 v214, v209, v128
	v_cvt_pk_bf16_f32 v128, v197, v198
	v_cvt_pk_bf16_f32 v130, v202, v204
	s_waitcnt lgkmcnt(1)
	v_mfma_f32_32x32x16_bf16 v[80:95], v[136:139], v[104:107], v[80:95]
	s_waitcnt lgkmcnt(0)
	v_mfma_f32_32x32x16_bf16 v[64:79], v[142:145], v[104:107], v[64:79]
	ds_read_b128 v[136:139], v159 offset:49152
	ds_read_b128 v[142:145], v159 offset:57344
	v_exp_f32_e32 v215, v132
	v_exp_f32_e32 v216, v133
	v_permlane32_swap_b32_e32 v128, v130
	v_add_f32_e32 v132, v215, v214
	v_add_f32_e32 v202, v216, v132
	v_permlane32_swap_b32_e32 v129, v131
	v_cvt_pk_bf16_f32 v132, v193, v194
	v_cvt_pk_bf16_f32 v133, v195, v196
	s_waitcnt lgkmcnt(1)
	v_mfma_f32_32x32x16_bf16 v[80:95], v[136:139], v[96:99], v[80:95]
	s_waitcnt lgkmcnt(0)
	v_mfma_f32_32x32x16_bf16 v[64:79], v[142:145], v[96:99], v[64:79]
	ds_read_b128 v[136:139], v180
	ds_read_b128 v[194:197], v180 offset:4096
	ds_read_b128 v[198:201], v153
	v_exp_f32_e32 v144, v134
	v_exp_f32_e32 v145, v135
	v_cvt_pk_bf16_f32 v135, v184, v192
	v_add_f32_e32 v134, v144, v202
	v_add_f32_e32 v142, v145, v134
	v_mov_b32_e32 v143, v142
	s_nop 1
	v_permlane32_swap_b32_e32 v142, v143
	v_cvt_pk_bf16_f32 v134, v182, v183
	s_waitcnt lgkmcnt(0)
	v_mfma_f32_32x32x16_bf16 v[80:95], v[136:139], v[198:201], v[80:95]
	v_mfma_f32_32x32x16_bf16 v[64:79], v[194:197], v[198:201], v[64:79]
	ds_read_b128 v[192:195], v179
	ds_read_b128 v[196:199], v179 offset:4096
	ds_read_b128 v[200:203], v153 offset:1024
	v_permlane32_swap_b32_e32 v132, v134
	v_permlane32_swap_b32_e32 v133, v135
	v_cvt_pk_bf16_f32 v136, v181, v190
	v_cvt_pk_bf16_f32 v137, v191, v205
	v_cvt_pk_bf16_f32 v138, v210, v211
	v_cvt_pk_bf16_f32 v139, v212, v213
	s_waitcnt lgkmcnt(0)
	v_mfma_f32_32x32x16_bf16 v[80:95], v[192:195], v[200:203], v[80:95]
	v_mfma_f32_32x32x16_bf16 v[64:79], v[196:199], v[200:203], v[64:79]
	ds_read_b128 v[192:195], v178
	ds_read_b128 v[196:199], v178 offset:4096
	ds_read_b128 v[200:203], v153 offset:2048
	v_permlane32_swap_b32_e32 v136, v138
	v_permlane32_swap_b32_e32 v137, v139
	v_cvt_pk_bf16_f32 v204, v206, v207
	v_cvt_pk_bf16_f32 v205, v208, v209
	v_cvt_pk_bf16_f32 v206, v215, v216
	v_cvt_pk_bf16_f32 v207, v144, v145
	s_waitcnt lgkmcnt(0)
	v_mfma_f32_32x32x16_bf16 v[80:95], v[192:195], v[200:203], v[80:95]
	v_mfma_f32_32x32x16_bf16 v[64:79], v[196:199], v[200:203], v[64:79]
	ds_read_b128 v[192:195], v177
	ds_read_b128 v[200:203], v177 offset:4096
	ds_read_b128 v[196:199], v153 offset:3072
	v_permlane32_swap_b32_e32 v204, v206
	v_permlane32_swap_b32_e32 v205, v207
	s_waitcnt lgkmcnt(0)
; #define SBAR() __builtin_amdgcn_sched_barrier(0)
; template <int OFF> __device__ __forceinline__ s16x4 tr_read(unsigned vb) { s16x4 r; asm volatile("ds_read_b64_tr_b16 %0, %1 offset:%2" : "=&v"(r) : "v"(vb), "i"(OFF) : "memory"); return r; }
; #define BARL() asm volatile("s_waitcnt lgkmcnt(0)\n\ts_barrier" ::: "memory")
; template <int D0> __device__ __forceinline__ void pv_one(f32x16& od, unsigned vb, bf16x8 pa0, bf16x8 pa1, bf16x8 pa2, bf16x8 pa3) {
;   const s16x4 l0 = tr_read<v_rd_off(D0, 0, 0)>(vb), h0 = tr_read<v_rd_off(D0, 0, 1)>(vb), l1 = tr_read<v_rd_off(D0, 1, 0)>(vb), h1 = tr_read<v_rd_off(D0, 1, 1)>(vb);
;   const s16x4 l2 = tr_read<v_rd_off(D0, 2, 0)>(vb), h2 = tr_read<v_rd_off(D0, 2, 1)>(vb), l3 = tr_read<v_rd_off(D0, 3, 0)>(vb), h3 = tr_read<v_rd_off(D0, 3, 1)>(vb);
;   asm volatile("s_waitcnt lgkmcnt(0)" ::: "memory"); SBAR();
;     ...
;   od = __builtin_amdgcn_mfma_f32_32x32x16_bf16(pa0, PK(l0, h0), od, 0, 0, 0);
;   od = __builtin_amdgcn_mfma_f32_32x32x16_bf16(pa1, PK(l1, h1), od, 0, 0, 0);
;   od = __builtin_amdgcn_mfma_f32_32x32x16_bf16(pa2, PK(l2, h2), od, 0, 0, 0);
;   od = __builtin_amdgcn_mfma_f32_32x32x16_bf16(pa3, PK(l3, h3), od, 0, 0, 0);
;     ...
; }
; __device__ __forceinline__ void pv_d0(f32x16* o, unsigned vb, bf16x8 pa0, bf16x8 pa1, bf16x8 pa2, bf16x8 pa3) {
;   pv_one<0>(o[0], vb, pa0, pa1, pa2, pa3); pv_one<1>(o[1], vb, pa0, pa1, pa2, pa3); pv_one<2>(o[2], vb, pa0, pa1, pa2, pa3); pv_one<3>(o[3], vb, pa0, pa1, pa2, pa3);
; }
; __device__ __forceinline__ void partialSM(f32x16& p0, f32x16& p1, float& m_reg, float& mn, float& alpha, float cadd) {
;   float pmax = p0[0];
; #pragma unroll
;   for (int r = 1; r < 16; ++r) pmax = fmaxf(pmax, p0[r]);
; #pragma unroll
;   for (int r = 0; r < 16; ++r) pmax = fmaxf(pmax, p1[r]);
;   { auto rr = __builtin_amdgcn_permlane32_swap(__float_as_uint(pmax), __float_as_uint(pmax), false, false);
;     pmax = fmaxf(__uint_as_float(rr[0]), __uint_as_float(rr[1])); }
;   pmax += cadd;
;   if (__builtin_expect(__all(pmax - m_reg <= THRL), 1)) { mn = m_reg; alpha = 1.f; }
;   else { mn = fmaxf(m_reg, pmax); alpha = __builtin_amdgcn_exp2f(m_reg - mn); m_reg = mn; }
; template <int MODE> ...
;     ...
;     pv_d0(o, vb0, pa0, pa1, pa2, pa3); BIAS(pB0, pB1, j * KVBLK, cadd); partialSM(pB0, pB1, m_reg, mnB, alB, cadd);
;     BARL();
;     DMA_K(j + 2, 1); DMA_V(j + 1, 0);
;     WAITV();
;     RESC(alB); BARL();
	v_mfma_f32_32x32x16_bf16 v[80:95], v[192:195], v[196:199], v[80:95]
	v_mfma_f32_32x32x16_bf16 v[64:79], v[200:203], v[196:199], v[64:79]
	ds_read_b64_tr_b16 v[192:193], v152 offset:0
	ds_read_b64_tr_b16 v[194:195], v152 offset:0x800
	ds_read_b64_tr_b16 v[196:197], v152 offset:0x1000
	ds_read_b64_tr_b16 v[198:199], v152 offset:0x1800
	ds_read_b64_tr_b16 v[200:201], v152 offset:0x2000
	ds_read_b64_tr_b16 v[202:203], v152 offset:0x2800
	ds_read_b64_tr_b16 v[208:209], v152 offset:0x3000
	ds_read_b64_tr_b16 v[210:211], v152 offset:0x3800
	s_waitcnt lgkmcnt(0)
	s_nop 0
	v_mfma_f32_32x32x16_bf16 v[0:15], v[128:131], v[192:195], v[0:15]
	ds_read_b64_tr_b16 v[192:193], v152 offset:0x200
	ds_read_b64_tr_b16 v[194:195], v152 offset:0xa00
	v_mfma_f32_32x32x16_bf16 v[0:15], v[132:135], v[196:199], v[0:15]
	ds_read_b64_tr_b16 v[196:197], v152 offset:0x1200
	ds_read_b64_tr_b16 v[198:199], v152 offset:0x1a00
	v_mfma_f32_32x32x16_bf16 v[0:15], v[136:139], v[200:203], v[0:15]
	ds_read_b64_tr_b16 v[200:201], v152 offset:0x2200
	ds_read_b64_tr_b16 v[202:203], v152 offset:0x2a00
	v_mfma_f32_32x32x16_bf16 v[0:15], v[204:207], v[208:211], v[0:15]
	ds_read_b64_tr_b16 v[208:209], v152 offset:0x3200
	ds_read_b64_tr_b16 v[210:211], v152 offset:0x3a00
	s_waitcnt lgkmcnt(0)
	v_mfma_f32_32x32x16_bf16 v[48:63], v[128:131], v[192:195], v[48:63]
	ds_read_b64_tr_b16 v[192:193], v152 offset:0x400
	ds_read_b64_tr_b16 v[194:195], v152 offset:0xc00
	v_mfma_f32_32x32x16_bf16 v[48:63], v[132:135], v[196:199], v[48:63]
	ds_read_b64_tr_b16 v[196:197], v152 offset:0x1400
	ds_read_b64_tr_b16 v[198:199], v152 offset:0x1c00
	v_mfma_f32_32x32x16_bf16 v[48:63], v[136:139], v[200:203], v[48:63]
	ds_read_b64_tr_b16 v[200:201], v152 offset:0x2400
	ds_read_b64_tr_b16 v[202:203], v152 offset:0x2c00
	v_mfma_f32_32x32x16_bf16 v[48:63], v[204:207], v[208:211], v[48:63]
	ds_read_b64_tr_b16 v[208:209], v152 offset:0x3400
	ds_read_b64_tr_b16 v[210:211], v152 offset:0x3c00
	s_waitcnt lgkmcnt(0)
	v_mfma_f32_32x32x16_bf16 v[32:47], v[128:131], v[192:195], v[32:47]
	ds_read_b64_tr_b16 v[192:193], v152 offset:0x600
	ds_read_b64_tr_b16 v[194:195], v152 offset:0xe00
	v_mfma_f32_32x32x16_bf16 v[32:47], v[132:135], v[196:199], v[32:47]
	ds_read_b64_tr_b16 v[196:197], v152 offset:0x1600
	ds_read_b64_tr_b16 v[198:199], v152 offset:0x1e00
	v_mfma_f32_32x32x16_bf16 v[32:47], v[136:139], v[200:203], v[32:47]
	ds_read_b64_tr_b16 v[200:201], v152 offset:0x2600
	ds_read_b64_tr_b16 v[202:203], v152 offset:0x2e00
	v_mfma_f32_32x32x16_bf16 v[32:47], v[204:207], v[208:211], v[32:47]
	ds_read_b64_tr_b16 v[208:209], v152 offset:0x3600
	ds_read_b64_tr_b16 v[210:211], v152 offset:0x3e00
	s_waitcnt lgkmcnt(0)
	v_mfma_f32_32x32x16_bf16 v[16:31], v[128:131], v[192:195], v[16:31]
	v_max_f32_e32 v128, v80, v81
	v_max3_f32 v128, v128, v82, v83
	v_max3_f32 v128, v128, v84, v85
	v_max3_f32 v128, v128, v86, v87
	v_max3_f32 v128, v128, v88, v89
	v_max3_f32 v128, v128, v90, v91
	v_max3_f32 v128, v128, v92, v93
	v_max3_f32 v128, v128, v94, v95
	v_max3_f32 v128, v128, v64, v65
	v_max3_f32 v128, v128, v66, v67
	v_max3_f32 v128, v128, v68, v69
	v_max3_f32 v128, v128, v70, v71
	v_max3_f32 v128, v128, v72, v73
	v_max3_f32 v128, v128, v74, v75
	v_max3_f32 v128, v128, v76, v77
	v_mfma_f32_32x32x16_bf16 v[16:31], v[132:135], v[196:199], v[16:31]
	v_max3_f32 v128, v128, v78, v79
	v_mov_b32_e32 v129, v128
	s_nop 1
	v_permlane32_swap_b32_e32 v128, v129
	v_max_f32_e32 v128, v128, v129
	v_sub_f32_e32 v129, v128, v174
	v_cmp_ge_f32_e32 vcc, s94, v129
	v_mfma_f32_32x32x16_bf16 v[16:31], v[136:139], v[200:203], v[16:31]
	s_cmp_eq_u64 vcc, exec
	s_cselect_b64 s[40:41], -1, 0
	s_add_u32 s27, s19, s18
	s_addc_u32 s30, s21, 0
	s_add_u32 s12, s27, 0x294c0000
	s_waitcnt lgkmcnt(0)
	s_barrier
	s_addc_u32 s13, s30, 0
	s_mov_b32 m0, s14
	s_nop 0
	global_load_lds_dwordx4 v155, s[12:13]
	s_add_u32 s12, s27, 0x294e0000
	s_addc_u32 s13, s30, 0
	s_mov_b32 m0, s15
	s_nop 0
	global_load_lds_dwordx4 v155, s[12:13]
	s_add_u32 s27, s24, s18
	v_mfma_f32_32x32x16_bf16 v[16:31], v[204:207], v[208:211], v[16:31]
	v_max_f32_e32 v128, v174, v128
	v_readlane_b32 s13, v253, 48
	s_mov_b32 m0, s13
	s_nop 0
	global_load_lds_dwordx4 v157, s[10:11]
	s_addc_u32 s30, s25, 0
	v_sub_f32_e32 v129, v174, v128
	s_add_u32 s12, s27, 0x31480000
	v_exp_f32_e32 v129, v129
	s_addc_u32 s13, s30, 0
	s_mov_b32 m0, s76
	s_nop 0
	global_load_lds_dwordx4 v156, s[12:13]
	s_add_u32 s12, s27, 0x314a0000
	s_addc_u32 s13, s30, 0
	s_mov_b32 m0, s89
	s_nop 0
	global_load_lds_dwordx4 v156, s[12:13]
	s_waitcnt vmcnt(5)
	v_cndmask_b32_e64 v144, v129, 1.0, s[40:41]
	v_cmp_gt_f32_e32 vcc, 1.0, v144
	s_cbranch_vccz .LBB0_943
	s_and_saveexec_b64 s[12:13], s[38:39]
	ds_write_b32 v154, v144
	s_or_b64 exec, exec, s[12:13]
	v_readlane_b32 s12, v253, 45
	s_waitcnt lgkmcnt(0)
	s_nop 1
	v_add_u32_e32 v129, s12, v140
	v_readlane_b32 s12, v253, 46
	s_nop 1
	v_add_u32_e32 v134, s12, v140
	v_readlane_b32 s12, v253, 44
	ds_read_b128 v[130:133], v129
	ds_read_b128 v[134:137], v134
	v_add_u32_e32 v129, s12, v140
	v_readlane_b32 s12, v253, 43
	ds_read_b128 v[192:195], v129
	s_waitcnt lgkmcnt(2)
	v_pk_mul_f32 v[8:9], v[8:9], v[130:131]
	v_add_u32_e32 v129, s12, v140
	ds_read_b128 v[196:199], v129
	s_waitcnt lgkmcnt(2)
	v_pk_mul_f32 v[12:13], v[12:13], v[134:135]
	s_waitcnt lgkmcnt(1)
	v_pk_mul_f32 v[4:5], v[4:5], v[192:193]
	v_pk_mul_f32 v[14:15], v[14:15], v[136:137]
	v_pk_mul_f32 v[10:11], v[10:11], v[132:133]
	v_pk_mul_f32 v[6:7], v[6:7], v[194:195]
	s_waitcnt lgkmcnt(0)
	v_pk_mul_f32 v[2:3], v[2:3], v[198:199]
	v_pk_mul_f32 v[0:1], v[0:1], v[196:197]
	v_pk_mul_f32 v[60:61], v[134:135], v[60:61]
	v_pk_mul_f32 v[56:57], v[130:131], v[56:57]
	v_pk_mul_f32 v[52:53], v[192:193], v[52:53]
	v_pk_mul_f32 v[62:63], v[136:137], v[62:63]
	v_pk_mul_f32 v[58:59], v[132:133], v[58:59]
	v_pk_mul_f32 v[54:55], v[194:195], v[54:55]
	v_pk_mul_f32 v[50:51], v[198:199], v[50:51]
	v_pk_mul_f32 v[48:49], v[196:197], v[48:49]
	v_pk_mul_f32 v[44:45], v[134:135], v[44:45]
	v_pk_mul_f32 v[40:41], v[130:131], v[40:41]
	v_pk_mul_f32 v[36:37], v[192:193], v[36:37]
	v_pk_mul_f32 v[46:47], v[136:137], v[46:47]
	v_pk_mul_f32 v[42:43], v[132:133], v[42:43]
	v_pk_mul_f32 v[38:39], v[194:195], v[38:39]
	v_pk_mul_f32 v[34:35], v[198:199], v[34:35]
	v_pk_mul_f32 v[32:33], v[196:197], v[32:33]
	v_pk_mul_f32 v[28:29], v[134:135], v[28:29]
	v_pk_mul_f32 v[24:25], v[130:131], v[24:25]
	v_pk_mul_f32 v[20:21], v[192:193], v[20:21]
	v_pk_mul_f32 v[30:31], v[136:137], v[30:31]
	v_pk_mul_f32 v[26:27], v[132:133], v[26:27]
	v_pk_mul_f32 v[22:23], v[194:195], v[22:23]
	v_pk_mul_f32 v[18:19], v[198:199], v[18:19]
	v_pk_mul_f32 v[16:17], v[196:197], v[16:17]
